# nt cache policy on the f32 weight-conversion tile loads (streamed once)
# speedup vs baseline: 1.0129x; 1.0129x over previous
; __device__ __forceinline__ void tr_load(const TrJob& jb, int tile, int tid, f32x4 (&v)[8][2], int& k0, int& n0) {
;     const int nblk = (jb.N + 127) / 128, kt = tile / nblk, nt = tile - kt * nblk; k0 = 256 * kt; n0 = 128 * nt;
;     const int c4 = (tid & 15) + 16 * ((tid >> 6) & 1), rp = ((tid >> 4) & 3) + 4 * (tid >> 7);
;     int col = n0 + 4 * c4; col = col < jb.N - 4 ? col : jb.N - 4;
;     const float* wp = jb.W + (size_t)(k0 + 2 * rp) * jb.N + col;
; #pragma unroll
;     for (int i = 0; i < 8; ++i) { v[i][0] = *(const f32x4*)(wp + (size_t)(32 * i) * jb.N); v[i][1] = *(const f32x4*)(wp + (size_t)(32 * i + 1) * jb.N); }
;     if (jb.gain) {
; #pragma unroll
;         for (int i = 0; i < 8; ++i) { const float ga = jb.gain[k0 + 32 * i + 2 * rp], gb = jb.gain[k0 + 32 * i + 2 * rp + 1]; v[i][0] = v[i][0] * ga; v[i][1] = v[i][1] * gb; } }
; }
.LBB0_82:
	s_add_i32 s7, s6, 0x7f
	s_lshr_b32 s8, s7, 7
	v_cvt_f32_u32_e32 v2, s8
	s_sub_i32 s11, 0, s8
	s_abs_i32 s10, s17
	s_ashr_i32 s9, s17, 31
	v_rcp_iflag_f32_e32 v2, v2
	v_lshrrev_b32_e32 v3, 4, v68
	v_ashrrev_i32_e32 v72, 5, v68
	v_bfi_b32 v3, 3, v3, v72
	v_mul_f32_e32 v2, 0x4f7ffffe, v2
	v_cvt_u32_f32_e32 v2, v2
	v_and_b32_e32 v70, 64, v68
	v_lshlrev_b32_e32 v78, 1, v3
	s_mov_b32 s7, 0
	v_readfirstlane_b32 s14, v2
	s_mul_i32 s11, s11, s14
	s_mul_hi_u32 s11, s14, s11
	s_add_i32 s14, s14, s11
	s_mul_hi_u32 s11, s10, s14
	s_mul_i32 s14, s11, s8
	s_sub_i32 s10, s10, s14
	s_add_i32 s15, s11, 1
	s_sub_i32 s14, s10, s8
	s_cmp_ge_u32 s10, s8
	s_cselect_b32 s11, s15, s11
	s_cselect_b32 s10, s14, s10
	s_add_i32 s14, s11, 1
	s_cmp_ge_u32 s10, s8
	s_cselect_b32 s10, s14, s11
	s_xor_b32 s10, s10, s9
	s_sub_i32 s9, s10, s9
	s_mul_i32 s8, s9, s8
	s_sub_i32 s8, s17, s8
	v_lshlrev_b32_e32 v2, 2, v68
	s_lshl_b32 s16, s9, 8
	s_lshl_b32 s17, s8, 7
	v_and_or_b32 v77, v2, 60, v70
	v_or_b32_e32 v2, s17, v77
	s_add_i32 s8, s6, -4
	v_add_u32_e32 v66, s16, v78
	v_min_i32_e32 v2, s8, v2
	v_mad_u64_u32 v[4:5], s[8:9], v66, s6, 0
	v_ashrrev_i32_e32 v67, 31, v66
	v_mov_b32_e32 v6, v5
	v_mad_u64_u32 v[6:7], s[8:9], v67, s6, v[6:7]
	v_mov_b32_e32 v5, v6
	v_lshl_add_u64 v[4:5], v[4:5], 2, s[4:5]
	v_ashrrev_i32_e32 v3, 31, v2
	v_lshl_add_u64 v[2:3], v[2:3], 2, v[4:5]
	s_lshl_b64 s[4:5], s[6:7], 2
	v_lshl_add_u64 v[10:11], v[2:3], 0, s[4:5]
	s_mul_i32 s8, s6, 0x7c
	s_mov_b32 s9, s7
	global_load_dwordx4 v[2:5], v[2:3], off nt
	s_nop 0
	global_load_dwordx4 v[6:9], v[10:11], off nt
	v_lshl_add_u64 v[10:11], v[10:11], 0, s[8:9]
	v_lshl_add_u64 v[18:19], v[10:11], 0, s[4:5]
	global_load_dwordx4 v[10:13], v[10:11], off nt
	s_nop 0
	global_load_dwordx4 v[14:17], v[18:19], off nt
	v_lshl_add_u64 v[18:19], v[18:19], 0, s[8:9]
	v_lshl_add_u64 v[26:27], v[18:19], 0, s[4:5]
	global_load_dwordx4 v[18:21], v[18:19], off nt
	s_nop 0
	global_load_dwordx4 v[22:25], v[26:27], off nt
	v_lshl_add_u64 v[26:27], v[26:27], 0, s[8:9]
	v_lshl_add_u64 v[34:35], v[26:27], 0, s[4:5]
	v_lshl_add_u64 v[38:39], v[34:35], 0, s[8:9]
	v_lshl_add_u64 v[42:43], v[38:39], 0, s[4:5]
	v_lshl_add_u64 v[46:47], v[42:43], 0, s[8:9]
	v_lshl_add_u64 v[50:51], v[46:47], 0, s[4:5]
	global_load_dwordx4 v[26:29], v[26:27], off nt
	s_nop 0
	global_load_dwordx4 v[30:33], v[34:35], off nt
	v_bfe_u32 v71, v68, 4, 2
	global_load_dwordx4 v[34:37], v[38:39], off nt
	s_cmp_eq_u64 s[12:13], 0
	global_load_dwordx4 v[38:41], v[42:43], off nt
	v_and_b32_e32 v72, -4, v72
	global_load_dwordx4 v[42:45], v[46:47], off nt
	v_readlane_b32 s95, v252, 41
	global_load_dwordx4 v[46:49], v[50:51], off nt
	v_lshl_add_u64 v[50:51], v[50:51], 0, s[8:9]
	v_lshl_add_u64 v[54:55], v[50:51], 0, s[4:5]
	v_lshl_add_u64 v[58:59], v[54:55], 0, s[8:9]
	v_lshl_add_u64 v[62:63], v[58:59], 0, s[4:5]
	global_load_dwordx4 v[50:53], v[50:51], off nt
	s_nop 0
	global_load_dwordx4 v[54:57], v[54:55], off nt
	s_nop 0
	global_load_dwordx4 v[58:61], v[58:59], off nt
	s_nop 0
	global_load_dwordx4 v[62:65], v[62:63], off nt
	s_cbranch_scc1 .LBB0_84
	v_lshl_add_u64 v[66:67], v[66:67], 2, s[12:13]
	global_load_dwordx2 v[74:75], v[66:67], off
	global_load_dwordx2 v[80:81], v[66:67], off offset:128
	global_load_dwordx2 v[82:83], v[66:67], off offset:256
	global_load_dwordx2 v[84:85], v[66:67], off offset:384
	global_load_dwordx2 v[86:87], v[66:67], off offset:512
	global_load_dwordx2 v[88:89], v[66:67], off offset:640
	global_load_dwordx2 v[90:91], v[66:67], off offset:768
	s_nop 0
	global_load_dwordx2 v[66:67], v[66:67], off offset:896
	s_waitcnt vmcnt(7)
	v_pk_mul_f32 v[4:5], v[4:5], v[74:75] op_sel_hi:[1,0]
	v_pk_mul_f32 v[2:3], v[2:3], v[74:75] op_sel_hi:[1,0]
	v_pk_mul_f32 v[8:9], v[8:9], v[74:75] op_sel:[0,1]
	v_pk_mul_f32 v[6:7], v[6:7], v[74:75] op_sel:[0,1]
	s_waitcnt vmcnt(6)
	v_pk_mul_f32 v[12:13], v[12:13], v[80:81] op_sel_hi:[1,0]
	v_pk_mul_f32 v[10:11], v[10:11], v[80:81] op_sel_hi:[1,0]
	v_pk_mul_f32 v[16:17], v[16:17], v[80:81] op_sel:[0,1]
	v_pk_mul_f32 v[14:15], v[14:15], v[80:81] op_sel:[0,1]
	s_waitcnt vmcnt(5)
	v_pk_mul_f32 v[20:21], v[20:21], v[82:83] op_sel_hi:[1,0]
	v_pk_mul_f32 v[18:19], v[18:19], v[82:83] op_sel_hi:[1,0]
	v_pk_mul_f32 v[24:25], v[24:25], v[82:83] op_sel:[0,1]
	v_pk_mul_f32 v[22:23], v[22:23], v[82:83] op_sel:[0,1]
	s_waitcnt vmcnt(4)
	v_pk_mul_f32 v[28:29], v[28:29], v[84:85] op_sel_hi:[1,0]
	v_pk_mul_f32 v[26:27], v[26:27], v[84:85] op_sel_hi:[1,0]
	v_pk_mul_f32 v[32:33], v[32:33], v[84:85] op_sel:[0,1]
	v_pk_mul_f32 v[30:31], v[30:31], v[84:85] op_sel:[0,1]
	s_waitcnt vmcnt(3)
	v_pk_mul_f32 v[36:37], v[36:37], v[86:87] op_sel_hi:[1,0]
	v_pk_mul_f32 v[34:35], v[34:35], v[86:87] op_sel_hi:[1,0]
	v_pk_mul_f32 v[40:41], v[40:41], v[86:87] op_sel:[0,1]
	v_pk_mul_f32 v[38:39], v[38:39], v[86:87] op_sel:[0,1]
	s_waitcnt vmcnt(2)
	v_pk_mul_f32 v[44:45], v[44:45], v[88:89] op_sel_hi:[1,0]
	v_pk_mul_f32 v[42:43], v[42:43], v[88:89] op_sel_hi:[1,0]
	v_pk_mul_f32 v[48:49], v[48:49], v[88:89] op_sel:[0,1]
	v_pk_mul_f32 v[46:47], v[46:47], v[88:89] op_sel:[0,1]
	s_waitcnt vmcnt(1)
	v_pk_mul_f32 v[52:53], v[52:53], v[90:91] op_sel_hi:[1,0]
	v_pk_mul_f32 v[50:51], v[50:51], v[90:91] op_sel_hi:[1,0]
	v_pk_mul_f32 v[56:57], v[56:57], v[90:91] op_sel:[0,1]
	v_pk_mul_f32 v[54:55], v[54:55], v[90:91] op_sel:[0,1]
	s_waitcnt vmcnt(0)
	v_pk_mul_f32 v[60:61], v[60:61], v[66:67] op_sel_hi:[1,0]
	v_pk_mul_f32 v[58:59], v[58:59], v[66:67] op_sel_hi:[1,0]
	v_pk_mul_f32 v[64:65], v[64:65], v[66:67] op_sel:[0,1]
	v_pk_mul_f32 v[62:63], v[62:63], v[66:67] op_sel:[0,1]

; __device__ __forceinline__ void tr_load(const TrJob& jb, int tile, int tid, f32x4 (&v)[8][2], int& k0, int& n0) {
;     const int nblk = (jb.N + 127) / 128, kt = tile / nblk, nt = tile - kt * nblk; k0 = 256 * kt; n0 = 128 * nt;
;     const int c4 = (tid & 15) + 16 * ((tid >> 6) & 1), rp = ((tid >> 4) & 3) + 4 * (tid >> 7);
;     int col = n0 + 4 * c4; col = col < jb.N - 4 ? col : jb.N - 4;
;     const float* wp = jb.W + (size_t)(k0 + 2 * rp) * jb.N + col;
; #pragma unroll
;     for (int i = 0; i < 8; ++i) { v[i][0] = *(const f32x4*)(wp + (size_t)(32 * i) * jb.N); v[i][1] = *(const f32x4*)(wp + (size_t)(32 * i + 1) * jb.N); }
;     if (jb.gain) {
; #pragma unroll
;         for (int i = 0; i < 8; ++i) { const float ga = jb.gain[k0 + 32 * i + 2 * rp], gb = jb.gain[k0 + 32 * i + 2 * rp + 1]; v[i][0] = v[i][0] * ga; v[i][1] = v[i][1] * gb; } }
; }
; __device__ __forceinline__ void conv_until(const Args& A, LAS unsigned char* lds, int limit, int extra) {
;     ...
;         if (Tn != 0xffffffffu) { conv_job(A, (int)Tn, jb, t); tr_load(jb, t, tid, v, k0, n0); }
.LBB0_125:
	s_add_i32 s12, s6, 0x7f
	s_lshr_b32 s12, s12, 7
	v_cvt_f32_u32_e32 v2, s12
	s_sub_i32 s17, 0, s12
	s_abs_i32 s16, s45
	s_ashr_i32 s13, s45, 31
	v_rcp_iflag_f32_e32 v2, v2
	s_nop 0
	v_mul_f32_e32 v2, 0x4f7ffffe, v2
	v_cvt_u32_f32_e32 v2, v2
	s_nop 0
	v_readfirstlane_b32 s18, v2
	s_mul_i32 s17, s17, s18
	s_mul_hi_u32 s17, s18, s17
	s_add_i32 s18, s18, s17
	s_mul_hi_u32 s17, s16, s18
	s_mul_i32 s18, s17, s12
	s_sub_i32 s16, s16, s18
	s_add_i32 s19, s17, 1
	s_sub_i32 s18, s16, s12
	s_cmp_ge_u32 s16, s12
	s_cselect_b32 s17, s19, s17
	s_cselect_b32 s16, s18, s16
	s_add_i32 s18, s17, 1
	s_cmp_ge_u32 s16, s12
	s_cselect_b32 s16, s18, s17
	s_xor_b32 s16, s16, s13
	s_sub_i32 s13, s16, s13
	s_mul_i32 s12, s13, s12
	s_lshl_b32 s16, s13, 8
	s_sub_i32 s12, s45, s12
	v_add_u32_e32 v66, s16, v78
	s_lshl_b32 s17, s12, 7
	v_mad_u64_u32 v[4:5], s[12:13], v66, s6, 0
	v_ashrrev_i32_e32 v67, 31, v66
	v_mov_b32_e32 v6, v5
	s_add_i32 s18, s6, -4
	v_or_b32_e32 v2, s17, v77
	v_mad_u64_u32 v[6:7], s[12:13], v67, s6, v[6:7]
	v_min_i32_e32 v2, s18, v2
	v_mov_b32_e32 v5, v6
	v_lshl_add_u64 v[4:5], v[4:5], 2, s[14:15]
	v_ashrrev_i32_e32 v3, 31, v2
	v_lshl_add_u64 v[2:3], v[2:3], 2, v[4:5]
	s_lshl_b64 s[12:13], s[6:7], 2
	v_lshl_add_u64 v[10:11], v[2:3], 0, s[12:13]
	s_mul_i32 s14, s6, 0x7c
	s_mov_b32 s15, s7
	global_load_dwordx4 v[2:5], v[2:3], off nt
	s_nop 0
	global_load_dwordx4 v[6:9], v[10:11], off nt
	v_lshl_add_u64 v[10:11], v[10:11], 0, s[14:15]
	v_lshl_add_u64 v[18:19], v[10:11], 0, s[12:13]
	global_load_dwordx4 v[10:13], v[10:11], off nt
	s_nop 0
	global_load_dwordx4 v[14:17], v[18:19], off nt
	v_lshl_add_u64 v[18:19], v[18:19], 0, s[14:15]
	v_lshl_add_u64 v[26:27], v[18:19], 0, s[12:13]
	global_load_dwordx4 v[18:21], v[18:19], off nt
	s_nop 0
	global_load_dwordx4 v[22:25], v[26:27], off nt
	v_lshl_add_u64 v[26:27], v[26:27], 0, s[14:15]
	v_lshl_add_u64 v[34:35], v[26:27], 0, s[12:13]
	v_lshl_add_u64 v[38:39], v[34:35], 0, s[14:15]
	v_lshl_add_u64 v[42:43], v[38:39], 0, s[12:13]
	v_lshl_add_u64 v[46:47], v[42:43], 0, s[14:15]
	v_lshl_add_u64 v[50:51], v[46:47], 0, s[12:13]
	v_lshl_add_u64 v[54:55], v[50:51], 0, s[14:15]
	v_lshl_add_u64 v[58:59], v[54:55], 0, s[12:13]
	v_lshl_add_u64 v[62:63], v[58:59], 0, s[14:15]
	global_load_dwordx4 v[26:29], v[26:27], off nt
	s_nop 0
	global_load_dwordx4 v[30:33], v[34:35], off nt
	s_cmp_eq_u64 s[10:11], 0
	global_load_dwordx4 v[34:37], v[38:39], off nt
	s_nop 0
	global_load_dwordx4 v[38:41], v[42:43], off nt
	s_nop 0
	global_load_dwordx4 v[42:45], v[46:47], off nt
	s_nop 0
	global_load_dwordx4 v[46:49], v[50:51], off nt
	s_nop 0
	global_load_dwordx4 v[50:53], v[54:55], off nt
	s_nop 0
	global_load_dwordx4 v[54:57], v[58:59], off nt
	s_nop 0
	global_load_dwordx4 v[58:61], v[62:63], off nt
	v_lshl_add_u64 v[62:63], v[62:63], 0, s[12:13]
	global_load_dwordx4 v[62:65], v[62:63], off nt
	s_cbranch_scc1 .LBB0_127
	v_lshl_add_u64 v[68:69], v[66:67], 2, s[10:11]
	v_add_u32_e32 v72, 32, v66
	v_add_u32_e32 v74, 64, v66
	v_add_u32_e32 v94, 0x60, v66
	v_add_u32_e32 v96, 0x80, v66
	v_add_u32_e32 v98, 0xa0, v66
	v_add_u32_e32 v100, 0xc0, v66
	v_add_u32_e32 v66, 0xe0, v66
	v_ashrrev_i32_e32 v73, 31, v72
	v_ashrrev_i32_e32 v75, 31, v74
	v_ashrrev_i32_e32 v95, 31, v94
	v_ashrrev_i32_e32 v97, 31, v96
	v_ashrrev_i32_e32 v99, 31, v98
	v_ashrrev_i32_e32 v101, 31, v100
	v_ashrrev_i32_e32 v67, 31, v66
	v_lshl_add_u64 v[72:73], v[72:73], 2, s[10:11]
	v_lshl_add_u64 v[74:75], v[74:75], 2, s[10:11]
	v_lshl_add_u64 v[94:95], v[94:95], 2, s[10:11]
	v_lshl_add_u64 v[96:97], v[96:97], 2, s[10:11]
	v_lshl_add_u64 v[98:99], v[98:99], 2, s[10:11]
	v_lshl_add_u64 v[100:101], v[100:101], 2, s[10:11]
	v_lshl_add_u64 v[66:67], v[66:67], 2, s[10:11]
	global_load_dwordx2 v[68:69], v[68:69], off
	s_nop 0
	global_load_dwordx2 v[72:73], v[72:73], off
	s_nop 0
	global_load_dwordx2 v[74:75], v[74:75], off
	s_waitcnt vmcnt(1)
	v_pk_mul_f32 v[12:13], v[12:13], v[72:73] op_sel_hi:[1,0]
	global_load_dwordx2 v[94:95], v[94:95], off
	v_pk_mul_f32 v[10:11], v[10:11], v[72:73] op_sel_hi:[1,0]
	global_load_dwordx2 v[96:97], v[96:97], off
	v_pk_mul_f32 v[16:17], v[16:17], v[72:73] op_sel:[0,1]
	global_load_dwordx2 v[98:99], v[98:99], off
	v_pk_mul_f32 v[14:15], v[14:15], v[72:73] op_sel:[0,1]
	global_load_dwordx2 v[100:101], v[100:101], off
	s_waitcnt vmcnt(4)
	v_pk_mul_f32 v[20:21], v[20:21], v[74:75] op_sel_hi:[1,0]
	global_load_dwordx2 v[66:67], v[66:67], off
	v_pk_mul_f32 v[4:5], v[4:5], v[68:69] op_sel_hi:[1,0]
	v_pk_mul_f32 v[2:3], v[2:3], v[68:69] op_sel_hi:[1,0]
	v_pk_mul_f32 v[8:9], v[8:9], v[68:69] op_sel:[0,1]
	v_pk_mul_f32 v[6:7], v[6:7], v[68:69] op_sel:[0,1]
	v_pk_mul_f32 v[18:19], v[18:19], v[74:75] op_sel_hi:[1,0]
	v_pk_mul_f32 v[24:25], v[24:25], v[74:75] op_sel:[0,1]
	v_pk_mul_f32 v[22:23], v[22:23], v[74:75] op_sel:[0,1]
	s_waitcnt vmcnt(4)
	v_pk_mul_f32 v[28:29], v[28:29], v[94:95] op_sel_hi:[1,0]
	v_pk_mul_f32 v[26:27], v[26:27], v[94:95] op_sel_hi:[1,0]
	v_pk_mul_f32 v[32:33], v[32:33], v[94:95] op_sel:[0,1]
	v_pk_mul_f32 v[30:31], v[30:31], v[94:95] op_sel:[0,1]
	s_waitcnt vmcnt(3)
	v_pk_mul_f32 v[36:37], v[36:37], v[96:97] op_sel_hi:[1,0]
	v_pk_mul_f32 v[34:35], v[34:35], v[96:97] op_sel_hi:[1,0]
	v_pk_mul_f32 v[40:41], v[40:41], v[96:97] op_sel:[0,1]
	v_pk_mul_f32 v[38:39], v[38:39], v[96:97] op_sel:[0,1]
	s_waitcnt vmcnt(2)
	v_pk_mul_f32 v[44:45], v[44:45], v[98:99] op_sel_hi:[1,0]
	v_pk_mul_f32 v[42:43], v[42:43], v[98:99] op_sel_hi:[1,0]
	v_pk_mul_f32 v[48:49], v[48:49], v[98:99] op_sel:[0,1]
	v_pk_mul_f32 v[46:47], v[46:47], v[98:99] op_sel:[0,1]
	s_waitcnt vmcnt(1)
	v_pk_mul_f32 v[52:53], v[52:53], v[100:101] op_sel_hi:[1,0]
	v_pk_mul_f32 v[50:51], v[50:51], v[100:101] op_sel_hi:[1,0]
	v_pk_mul_f32 v[56:57], v[56:57], v[100:101] op_sel:[0,1]
	v_pk_mul_f32 v[54:55], v[54:55], v[100:101] op_sel:[0,1]
	s_waitcnt vmcnt(0)
	v_pk_mul_f32 v[60:61], v[60:61], v[66:67] op_sel_hi:[1,0]
	v_pk_mul_f32 v[58:59], v[58:59], v[66:67] op_sel_hi:[1,0]
	v_pk_mul_f32 v[64:65], v[64:65], v[66:67] op_sel:[0,1]
	v_pk_mul_f32 v[62:63], v[62:63], v[66:67] op_sel:[0,1]

; __device__ __forceinline__ void tr_load(const TrJob& jb, int tile, int tid, f32x4 (&v)[8][2], int& k0, int& n0) {
;     const int nblk = (jb.N + 127) / 128, kt = tile / nblk, nt = tile - kt * nblk; k0 = 256 * kt; n0 = 128 * nt;
;     const int c4 = (tid & 15) + 16 * ((tid >> 6) & 1), rp = ((tid >> 4) & 3) + 4 * (tid >> 7);
;     int col = n0 + 4 * c4; col = col < jb.N - 4 ? col : jb.N - 4;
;     const float* wp = jb.W + (size_t)(k0 + 2 * rp) * jb.N + col;
; #pragma unroll
;     for (int i = 0; i < 8; ++i) { v[i][0] = *(const f32x4*)(wp + (size_t)(32 * i) * jb.N); v[i][1] = *(const f32x4*)(wp + (size_t)(32 * i + 1) * jb.N); }
;     if (jb.gain) {
; #pragma unroll
;         for (int i = 0; i < 8; ++i) { const float ga = jb.gain[k0 + 32 * i + 2 * rp], gb = jb.gain[k0 + 32 * i + 2 * rp + 1]; v[i][0] = v[i][0] * ga; v[i][1] = v[i][1] * gb; } }
; }
.LBB0_343:
	s_add_i32 s6, s34, 0x7f
	s_lshr_b32 s6, s6, 7
	v_cvt_f32_u32_e32 v4, s6
	s_sub_i32 s9, 0, s6
	s_abs_i32 s8, s15
	s_ashr_i32 s7, s15, 31
	v_rcp_iflag_f32_e32 v4, v4
	v_lshrrev_b32_e32 v5, 4, v2
	v_ashrrev_i32_e32 v71, 5, v2
	v_bfi_b32 v5, 3, v5, v71
	v_mul_f32_e32 v4, 0x4f7ffffe, v4
	v_cvt_u32_f32_e32 v4, v4
	v_and_b32_e32 v70, 64, v2
	v_lshlrev_b32_e32 v78, 1, v5
	v_readfirstlane_b32 s12, v4
	s_mul_i32 s9, s9, s12
	s_mul_hi_u32 s9, s12, s9
	s_add_i32 s12, s12, s9
	s_mul_hi_u32 s9, s8, s12
	s_mul_i32 s12, s9, s6
	s_sub_i32 s8, s8, s12
	s_add_i32 s13, s9, 1
	s_sub_i32 s12, s8, s6
	s_cmp_ge_u32 s8, s6
	s_cselect_b32 s9, s13, s9
	s_cselect_b32 s8, s12, s8
	s_add_i32 s12, s9, 1
	s_cmp_ge_u32 s8, s6
	s_cselect_b32 s8, s12, s9
	s_xor_b32 s8, s8, s7
	s_sub_i32 s7, s8, s7
	s_mul_i32 s6, s7, s6
	s_sub_i32 s6, s15, s6
	v_lshlrev_b32_e32 v4, 2, v2
	s_lshl_b32 s14, s7, 8
	s_lshl_b32 s15, s6, 7
	v_and_or_b32 v77, v4, 60, v70
	v_or_b32_e32 v4, s15, v77
	s_add_i32 s6, s34, -4
	v_add_u32_e32 v68, s14, v78
	v_min_i32_e32 v4, s6, v4
	s_waitcnt vmcnt(12)
	v_mad_u64_u32 v[6:7], s[6:7], v68, s34, 0
	v_ashrrev_i32_e32 v69, 31, v68
	v_mov_b32_e32 v8, v7
	v_mad_u64_u32 v[8:9], s[6:7], v69, s34, v[8:9]
	v_mov_b32_e32 v7, v8
	v_lshl_add_u64 v[6:7], v[6:7], 2, s[4:5]
	v_ashrrev_i32_e32 v5, 31, v4
	v_lshl_add_u64 v[4:5], v[4:5], 2, v[6:7]
	s_lshl_b64 s[4:5], s[34:35], 2
	s_waitcnt vmcnt(11)
	v_lshl_add_u64 v[12:13], v[4:5], 0, s[4:5]
	s_mul_i32 s6, s34, 0x7c
	s_mov_b32 s7, s35
	global_load_dwordx4 v[4:7], v[4:5], off nt
	s_nop 0
	global_load_dwordx4 v[8:11], v[12:13], off nt
	v_lshl_add_u64 v[12:13], v[12:13], 0, s[6:7]
	s_waitcnt vmcnt(11)
	v_lshl_add_u64 v[20:21], v[12:13], 0, s[4:5]
	global_load_dwordx4 v[12:15], v[12:13], off nt
	s_nop 0
	global_load_dwordx4 v[16:19], v[20:21], off nt
	v_lshl_add_u64 v[20:21], v[20:21], 0, s[6:7]
	s_waitcnt vmcnt(12)
	v_lshl_add_u64 v[28:29], v[20:21], 0, s[4:5]
	global_load_dwordx4 v[20:23], v[20:21], off nt
	s_nop 0
	global_load_dwordx4 v[24:27], v[28:29], off nt
	v_lshl_add_u64 v[28:29], v[28:29], 0, s[6:7]
	s_waitcnt vmcnt(13)
	v_lshl_add_u64 v[36:37], v[28:29], 0, s[4:5]
	s_waitcnt vmcnt(12)
	v_lshl_add_u64 v[40:41], v[36:37], 0, s[6:7]
	s_waitcnt vmcnt(11)
	v_lshl_add_u64 v[44:45], v[40:41], 0, s[4:5]
	s_waitcnt vmcnt(10)
	v_lshl_add_u64 v[48:49], v[44:45], 0, s[6:7]
	s_waitcnt vmcnt(9)
	v_lshl_add_u64 v[52:53], v[48:49], 0, s[4:5]
	s_waitcnt vmcnt(8)
	v_lshl_add_u64 v[56:57], v[52:53], 0, s[6:7]
	s_waitcnt vmcnt(7)
	v_lshl_add_u64 v[60:61], v[56:57], 0, s[4:5]
	s_waitcnt vmcnt(6)
	v_lshl_add_u64 v[64:65], v[60:61], 0, s[6:7]
	global_load_dwordx4 v[28:31], v[28:29], off nt
	s_nop 0
	global_load_dwordx4 v[32:35], v[36:37], off nt
	s_cmp_eq_u64 s[10:11], 0
	global_load_dwordx4 v[36:39], v[40:41], off nt
	s_nop 0
	global_load_dwordx4 v[40:43], v[44:45], off nt
	s_nop 0
	global_load_dwordx4 v[44:47], v[48:49], off nt
	s_nop 0
	global_load_dwordx4 v[48:51], v[52:53], off nt
	s_nop 0
	global_load_dwordx4 v[52:55], v[56:57], off nt
	s_nop 0
	global_load_dwordx4 v[56:59], v[60:61], off nt
	s_nop 0
	global_load_dwordx4 v[60:63], v[64:65], off nt
	v_lshl_add_u64 v[64:65], v[64:65], 0, s[4:5]
	global_load_dwordx4 v[64:67], v[64:65], off nt
	s_cbranch_scc1 .LBB0_345
	v_lshl_add_u64 v[68:69], v[68:69], 2, s[10:11]
	global_load_dwordx2 v[72:73], v[68:69], off
	s_waitcnt vmcnt(0)
	v_pk_mul_f32 v[6:7], v[6:7], v[72:73] op_sel_hi:[1,0]
	v_pk_mul_f32 v[4:5], v[4:5], v[72:73] op_sel_hi:[1,0]
	v_pk_mul_f32 v[10:11], v[10:11], v[72:73] op_sel:[0,1]
	v_pk_mul_f32 v[8:9], v[8:9], v[72:73] op_sel:[0,1]
	global_load_dwordx2 v[72:73], v[68:69], off offset:128
	s_waitcnt vmcnt(0)
	v_pk_mul_f32 v[14:15], v[14:15], v[72:73] op_sel_hi:[1,0]
	v_pk_mul_f32 v[12:13], v[12:13], v[72:73] op_sel_hi:[1,0]
	v_pk_mul_f32 v[18:19], v[18:19], v[72:73] op_sel:[0,1]
	v_pk_mul_f32 v[16:17], v[16:17], v[72:73] op_sel:[0,1]
	global_load_dwordx2 v[72:73], v[68:69], off offset:256
	s_waitcnt vmcnt(0)
	v_pk_mul_f32 v[22:23], v[22:23], v[72:73] op_sel_hi:[1,0]
	v_pk_mul_f32 v[20:21], v[20:21], v[72:73] op_sel_hi:[1,0]
	v_pk_mul_f32 v[26:27], v[26:27], v[72:73] op_sel:[0,1]
	v_pk_mul_f32 v[24:25], v[24:25], v[72:73] op_sel:[0,1]
	global_load_dwordx2 v[72:73], v[68:69], off offset:384
	s_waitcnt vmcnt(0)
	v_pk_mul_f32 v[30:31], v[30:31], v[72:73] op_sel_hi:[1,0]
	v_pk_mul_f32 v[28:29], v[28:29], v[72:73] op_sel_hi:[1,0]
	v_pk_mul_f32 v[34:35], v[34:35], v[72:73] op_sel:[0,1]
	v_pk_mul_f32 v[32:33], v[32:33], v[72:73] op_sel:[0,1]
	global_load_dwordx2 v[72:73], v[68:69], off offset:512
	s_waitcnt vmcnt(0)
	v_pk_mul_f32 v[38:39], v[38:39], v[72:73] op_sel_hi:[1,0]
	v_pk_mul_f32 v[36:37], v[36:37], v[72:73] op_sel_hi:[1,0]
	v_pk_mul_f32 v[42:43], v[42:43], v[72:73] op_sel:[0,1]
	v_pk_mul_f32 v[40:41], v[40:41], v[72:73] op_sel:[0,1]
	global_load_dwordx2 v[72:73], v[68:69], off offset:640
	s_waitcnt vmcnt(0)
	v_pk_mul_f32 v[46:47], v[46:47], v[72:73] op_sel_hi:[1,0]
	v_pk_mul_f32 v[44:45], v[44:45], v[72:73] op_sel_hi:[1,0]
	v_pk_mul_f32 v[50:51], v[50:51], v[72:73] op_sel:[0,1]
	v_pk_mul_f32 v[48:49], v[48:49], v[72:73] op_sel:[0,1]
	global_load_dwordx2 v[72:73], v[68:69], off offset:768
	s_waitcnt vmcnt(0)
	v_pk_mul_f32 v[54:55], v[54:55], v[72:73] op_sel_hi:[1,0]
	global_load_dwordx2 v[68:69], v[68:69], off offset:896
	v_pk_mul_f32 v[52:53], v[52:53], v[72:73] op_sel_hi:[1,0]
	v_pk_mul_f32 v[58:59], v[58:59], v[72:73] op_sel:[0,1]
	v_pk_mul_f32 v[56:57], v[56:57], v[72:73] op_sel:[0,1]
	s_waitcnt vmcnt(0)
	v_pk_mul_f32 v[62:63], v[62:63], v[68:69] op_sel_hi:[1,0]
	v_pk_mul_f32 v[60:61], v[60:61], v[68:69] op_sel_hi:[1,0]
	v_pk_mul_f32 v[66:67], v[66:67], v[68:69] op_sel:[0,1]
	v_pk_mul_f32 v[64:65], v[64:65], v[68:69] op_sel:[0,1]

; __device__ __forceinline__ void tr_load(const TrJob& jb, int tile, int tid, f32x4 (&v)[8][2], int& k0, int& n0) {
;     const int nblk = (jb.N + 127) / 128, kt = tile / nblk, nt = tile - kt * nblk; k0 = 256 * kt; n0 = 128 * nt;
;     const int c4 = (tid & 15) + 16 * ((tid >> 6) & 1), rp = ((tid >> 4) & 3) + 4 * (tid >> 7);
;     int col = n0 + 4 * c4; col = col < jb.N - 4 ? col : jb.N - 4;
;     const float* wp = jb.W + (size_t)(k0 + 2 * rp) * jb.N + col;
; #pragma unroll
;     for (int i = 0; i < 8; ++i) { v[i][0] = *(const f32x4*)(wp + (size_t)(32 * i) * jb.N); v[i][1] = *(const f32x4*)(wp + (size_t)(32 * i + 1) * jb.N); }
;     if (jb.gain) {
; #pragma unroll
;         for (int i = 0; i < 8; ++i) { const float ga = jb.gain[k0 + 32 * i + 2 * rp], gb = jb.gain[k0 + 32 * i + 2 * rp + 1]; v[i][0] = v[i][0] * ga; v[i][1] = v[i][1] * gb; } }
; }
.LBB0_385:
	s_add_i32 s10, s34, 0x7f
	s_lshr_b32 s10, s10, 7
	v_cvt_f32_u32_e32 v2, s10
	s_sub_i32 s15, 0, s10
	s_abs_i32 s14, s40
	s_ashr_i32 s11, s40, 31
	v_rcp_iflag_f32_e32 v2, v2
	s_nop 0
	v_mul_f32_e32 v2, 0x4f7ffffe, v2
	v_cvt_u32_f32_e32 v2, v2
	s_nop 0
	v_readfirstlane_b32 s16, v2
	s_mul_i32 s15, s15, s16
	s_mul_hi_u32 s15, s16, s15
	s_add_i32 s16, s16, s15
	s_mul_hi_u32 s15, s14, s16
	s_mul_i32 s16, s15, s10
	s_sub_i32 s14, s14, s16
	s_add_i32 s17, s15, 1
	s_sub_i32 s16, s14, s10
	s_cmp_ge_u32 s14, s10
	s_cselect_b32 s15, s17, s15
	s_cselect_b32 s14, s16, s14
	s_add_i32 s16, s15, 1
	s_cmp_ge_u32 s14, s10
	s_cselect_b32 s14, s16, s15
	s_xor_b32 s14, s14, s11
	s_sub_i32 s11, s14, s11
	s_mul_i32 s10, s11, s10
	s_lshl_b32 s14, s11, 8
	s_sub_i32 s10, s40, s10
	v_add_u32_e32 v68, s14, v78
	s_lshl_b32 s15, s10, 7
	s_add_i32 s16, s34, -4
	v_or_b32_e32 v2, s15, v77
	v_mad_u64_u32 v[6:7], s[10:11], v68, s34, 0
	v_ashrrev_i32_e32 v69, 31, v68
	v_min_i32_e32 v4, s16, v2
	v_mov_b32_e32 v2, v7
	v_mad_u64_u32 v[8:9], s[10:11], v69, s34, v[2:3]
	v_mov_b32_e32 v7, v8
	v_lshl_add_u64 v[6:7], v[6:7], 2, s[12:13]
	v_ashrrev_i32_e32 v5, 31, v4
	v_lshl_add_u64 v[4:5], v[4:5], 2, v[6:7]
	s_lshl_b64 s[10:11], s[34:35], 2
	v_lshl_add_u64 v[12:13], v[4:5], 0, s[10:11]
	s_mul_i32 s12, s34, 0x7c
	s_mov_b32 s13, s35
	global_load_dwordx4 v[4:7], v[4:5], off nt
	s_nop 0
	global_load_dwordx4 v[8:11], v[12:13], off nt
	v_lshl_add_u64 v[12:13], v[12:13], 0, s[12:13]
	v_lshl_add_u64 v[20:21], v[12:13], 0, s[10:11]
	global_load_dwordx4 v[12:15], v[12:13], off nt
	s_nop 0
	global_load_dwordx4 v[16:19], v[20:21], off nt
	v_lshl_add_u64 v[20:21], v[20:21], 0, s[12:13]
	v_lshl_add_u64 v[28:29], v[20:21], 0, s[10:11]
	global_load_dwordx4 v[20:23], v[20:21], off nt
	s_nop 0
	global_load_dwordx4 v[24:27], v[28:29], off nt
	v_lshl_add_u64 v[28:29], v[28:29], 0, s[12:13]
	v_lshl_add_u64 v[36:37], v[28:29], 0, s[10:11]
	v_lshl_add_u64 v[40:41], v[36:37], 0, s[12:13]
	v_lshl_add_u64 v[44:45], v[40:41], 0, s[10:11]
	v_lshl_add_u64 v[48:49], v[44:45], 0, s[12:13]
	v_lshl_add_u64 v[52:53], v[48:49], 0, s[10:11]
	v_lshl_add_u64 v[56:57], v[52:53], 0, s[12:13]
	v_lshl_add_u64 v[60:61], v[56:57], 0, s[10:11]
	v_lshl_add_u64 v[64:65], v[60:61], 0, s[12:13]
	global_load_dwordx4 v[28:31], v[28:29], off nt
	s_nop 0
	global_load_dwordx4 v[32:35], v[36:37], off nt
	s_cmp_eq_u64 s[8:9], 0
	global_load_dwordx4 v[36:39], v[40:41], off nt
	s_nop 0
	global_load_dwordx4 v[40:43], v[44:45], off nt
	s_nop 0
	global_load_dwordx4 v[44:47], v[48:49], off nt
	s_nop 0
	global_load_dwordx4 v[48:51], v[52:53], off nt
	s_nop 0
	global_load_dwordx4 v[52:55], v[56:57], off nt
	s_nop 0
	global_load_dwordx4 v[56:59], v[60:61], off nt
	s_nop 0
	global_load_dwordx4 v[60:63], v[64:65], off nt
	v_lshl_add_u64 v[64:65], v[64:65], 0, s[10:11]
	global_load_dwordx4 v[64:67], v[64:65], off nt
	s_cbranch_scc1 .LBB0_387
	v_lshl_add_u64 v[70:71], v[68:69], 2, s[8:9]
	global_load_dwordx2 v[70:71], v[70:71], off
	s_waitcnt vmcnt(0)
	v_pk_mul_f32 v[6:7], v[6:7], v[70:71] op_sel_hi:[1,0]
	v_pk_mul_f32 v[4:5], v[4:5], v[70:71] op_sel_hi:[1,0]
	v_pk_mul_f32 v[10:11], v[10:11], v[70:71] op_sel:[0,1]
	v_pk_mul_f32 v[8:9], v[8:9], v[70:71] op_sel:[0,1]
	v_add_u32_e32 v70, 32, v68
	v_ashrrev_i32_e32 v71, 31, v70
	v_lshl_add_u64 v[70:71], v[70:71], 2, s[8:9]
	global_load_dwordx2 v[70:71], v[70:71], off
	s_waitcnt vmcnt(0)
	v_pk_mul_f32 v[14:15], v[14:15], v[70:71] op_sel_hi:[1,0]
	v_pk_mul_f32 v[12:13], v[12:13], v[70:71] op_sel_hi:[1,0]
	v_pk_mul_f32 v[18:19], v[18:19], v[70:71] op_sel:[0,1]
	v_pk_mul_f32 v[16:17], v[16:17], v[70:71] op_sel:[0,1]
	v_add_u32_e32 v70, 64, v68
	v_ashrrev_i32_e32 v71, 31, v70
	v_lshl_add_u64 v[70:71], v[70:71], 2, s[8:9]
	global_load_dwordx2 v[70:71], v[70:71], off
	s_waitcnt vmcnt(0)
	v_pk_mul_f32 v[22:23], v[22:23], v[70:71] op_sel_hi:[1,0]
	v_pk_mul_f32 v[20:21], v[20:21], v[70:71] op_sel_hi:[1,0]
	v_pk_mul_f32 v[26:27], v[26:27], v[70:71] op_sel:[0,1]
	v_pk_mul_f32 v[24:25], v[24:25], v[70:71] op_sel:[0,1]
	v_add_u32_e32 v70, 0x60, v68
	v_ashrrev_i32_e32 v71, 31, v70
	v_lshl_add_u64 v[70:71], v[70:71], 2, s[8:9]
	global_load_dwordx2 v[70:71], v[70:71], off
	s_waitcnt vmcnt(0)
	v_pk_mul_f32 v[30:31], v[30:31], v[70:71] op_sel_hi:[1,0]
	v_pk_mul_f32 v[28:29], v[28:29], v[70:71] op_sel_hi:[1,0]
	v_pk_mul_f32 v[34:35], v[34:35], v[70:71] op_sel:[0,1]
	v_pk_mul_f32 v[32:33], v[32:33], v[70:71] op_sel:[0,1]
	v_add_u32_e32 v70, 0x80, v68
	v_ashrrev_i32_e32 v71, 31, v70
	v_lshl_add_u64 v[70:71], v[70:71], 2, s[8:9]
	global_load_dwordx2 v[70:71], v[70:71], off
	s_waitcnt vmcnt(0)
	v_pk_mul_f32 v[38:39], v[38:39], v[70:71] op_sel_hi:[1,0]
	v_pk_mul_f32 v[36:37], v[36:37], v[70:71] op_sel_hi:[1,0]
	v_pk_mul_f32 v[42:43], v[42:43], v[70:71] op_sel:[0,1]
	v_pk_mul_f32 v[40:41], v[40:41], v[70:71] op_sel:[0,1]
	v_add_u32_e32 v70, 0xa0, v68
	v_ashrrev_i32_e32 v71, 31, v70
	v_lshl_add_u64 v[70:71], v[70:71], 2, s[8:9]
	global_load_dwordx2 v[70:71], v[70:71], off
	s_waitcnt vmcnt(0)
	v_pk_mul_f32 v[46:47], v[46:47], v[70:71] op_sel_hi:[1,0]
	v_pk_mul_f32 v[44:45], v[44:45], v[70:71] op_sel_hi:[1,0]
	v_pk_mul_f32 v[50:51], v[50:51], v[70:71] op_sel:[0,1]
	v_pk_mul_f32 v[48:49], v[48:49], v[70:71] op_sel:[0,1]
	v_add_u32_e32 v70, 0xc0, v68
	v_add_u32_e32 v68, 0xe0, v68
	v_ashrrev_i32_e32 v71, 31, v70
	v_ashrrev_i32_e32 v69, 31, v68
	v_lshl_add_u64 v[70:71], v[70:71], 2, s[8:9]
	v_lshl_add_u64 v[68:69], v[68:69], 2, s[8:9]
	global_load_dwordx2 v[70:71], v[70:71], off
	s_nop 0
	global_load_dwordx2 v[68:69], v[68:69], off
	s_waitcnt vmcnt(1)
	v_pk_mul_f32 v[54:55], v[54:55], v[70:71] op_sel_hi:[1,0]
	v_pk_mul_f32 v[52:53], v[52:53], v[70:71] op_sel_hi:[1,0]
	v_pk_mul_f32 v[58:59], v[58:59], v[70:71] op_sel:[0,1]
	v_pk_mul_f32 v[56:57], v[56:57], v[70:71] op_sel:[0,1]
	s_waitcnt vmcnt(0)
	v_pk_mul_f32 v[62:63], v[62:63], v[68:69] op_sel_hi:[1,0]
	v_pk_mul_f32 v[60:61], v[60:61], v[68:69] op_sel_hi:[1,0]
	v_pk_mul_f32 v[66:67], v[66:67], v[68:69] op_sel:[0,1]
	v_pk_mul_f32 v[64:65], v[64:65], v[68:69] op_sel:[0,1]

; __device__ __forceinline__ void tr_load(const TrJob& jb, int tile, int tid, f32x4 (&v)[8][2], int& k0, int& n0) {
;     const int nblk = (jb.N + 127) / 128, kt = tile / nblk, nt = tile - kt * nblk; k0 = 256 * kt; n0 = 128 * nt;
;     const int c4 = (tid & 15) + 16 * ((tid >> 6) & 1), rp = ((tid >> 4) & 3) + 4 * (tid >> 7);
;     int col = n0 + 4 * c4; col = col < jb.N - 4 ? col : jb.N - 4;
;     const float* wp = jb.W + (size_t)(k0 + 2 * rp) * jb.N + col;
; #pragma unroll
;     for (int i = 0; i < 8; ++i) { v[i][0] = *(const f32x4*)(wp + (size_t)(32 * i) * jb.N); v[i][1] = *(const f32x4*)(wp + (size_t)(32 * i + 1) * jb.N); }
;     if (jb.gain) {
; #pragma unroll
;         for (int i = 0; i < 8; ++i) { const float ga = jb.gain[k0 + 32 * i + 2 * rp], gb = jb.gain[k0 + 32 * i + 2 * rp + 1]; v[i][0] = v[i][0] * ga; v[i][1] = v[i][1] * gb; } }
; }
.LBB0_1079:
	s_add_i32 s10, s34, 0x7f
	s_lshr_b32 s10, s10, 7
	v_cvt_f32_u32_e32 v2, s10
	s_sub_i32 s15, 0, s10
	s_abs_i32 s14, s30
	s_ashr_i32 s11, s30, 31
	v_rcp_iflag_f32_e32 v2, v2
	s_nop 0
	v_mul_f32_e32 v2, 0x4f7ffffe, v2
	v_cvt_u32_f32_e32 v2, v2
	s_nop 0
	v_readfirstlane_b32 s16, v2
	s_mul_i32 s15, s15, s16
	s_mul_hi_u32 s15, s16, s15
	s_add_i32 s16, s16, s15
	s_mul_hi_u32 s15, s14, s16
	s_mul_i32 s16, s15, s10
	s_sub_i32 s14, s14, s16
	s_add_i32 s17, s15, 1
	s_sub_i32 s16, s14, s10
	s_cmp_ge_u32 s14, s10
	s_cselect_b32 s15, s17, s15
	s_cselect_b32 s14, s16, s14
	s_add_i32 s16, s15, 1
	s_cmp_ge_u32 s14, s10
	s_cselect_b32 s14, s16, s15
	s_xor_b32 s14, s14, s11
	s_sub_i32 s11, s14, s11
	s_mul_i32 s10, s11, s10
	s_lshl_b32 s14, s11, 8
	s_sub_i32 s10, s30, s10
	v_add_u32_e32 v68, s14, v78
	s_lshl_b32 s15, s10, 7
	s_add_i32 s16, s34, -4
	v_or_b32_e32 v2, s15, v77
	v_mad_u64_u32 v[6:7], s[10:11], v68, s34, 0
	v_ashrrev_i32_e32 v69, 31, v68
	v_min_i32_e32 v4, s16, v2
	v_mov_b32_e32 v2, v7
	v_mad_u64_u32 v[8:9], s[10:11], v69, s34, v[2:3]
	v_mov_b32_e32 v7, v8
	v_lshl_add_u64 v[6:7], v[6:7], 2, s[12:13]
	v_ashrrev_i32_e32 v5, 31, v4
	v_lshl_add_u64 v[4:5], v[4:5], 2, v[6:7]
	s_lshl_b64 s[10:11], s[34:35], 2
	v_lshl_add_u64 v[12:13], v[4:5], 0, s[10:11]
	s_mul_i32 s12, s34, 0x7c
	s_mov_b32 s13, s35
	global_load_dwordx4 v[4:7], v[4:5], off nt
	s_nop 0
	global_load_dwordx4 v[8:11], v[12:13], off nt
	v_lshl_add_u64 v[12:13], v[12:13], 0, s[12:13]
	v_lshl_add_u64 v[20:21], v[12:13], 0, s[10:11]
	global_load_dwordx4 v[12:15], v[12:13], off nt
	s_nop 0
	global_load_dwordx4 v[16:19], v[20:21], off nt
	v_lshl_add_u64 v[20:21], v[20:21], 0, s[12:13]
	v_lshl_add_u64 v[28:29], v[20:21], 0, s[10:11]
	global_load_dwordx4 v[20:23], v[20:21], off nt
	s_nop 0
	global_load_dwordx4 v[24:27], v[28:29], off nt
	v_lshl_add_u64 v[28:29], v[28:29], 0, s[12:13]
	v_lshl_add_u64 v[36:37], v[28:29], 0, s[10:11]
	v_lshl_add_u64 v[40:41], v[36:37], 0, s[12:13]
	v_lshl_add_u64 v[44:45], v[40:41], 0, s[10:11]
	v_lshl_add_u64 v[48:49], v[44:45], 0, s[12:13]
	v_lshl_add_u64 v[52:53], v[48:49], 0, s[10:11]
	v_lshl_add_u64 v[56:57], v[52:53], 0, s[12:13]
	v_lshl_add_u64 v[60:61], v[56:57], 0, s[10:11]
	v_lshl_add_u64 v[64:65], v[60:61], 0, s[12:13]
	global_load_dwordx4 v[28:31], v[28:29], off nt
	s_nop 0
	global_load_dwordx4 v[32:35], v[36:37], off nt
	s_cmp_eq_u64 s[8:9], 0
	global_load_dwordx4 v[36:39], v[40:41], off nt
	s_nop 0
	global_load_dwordx4 v[40:43], v[44:45], off nt
	s_nop 0
	global_load_dwordx4 v[44:47], v[48:49], off nt
	s_nop 0
	global_load_dwordx4 v[48:51], v[52:53], off nt
	s_nop 0
	global_load_dwordx4 v[52:55], v[56:57], off nt
	s_nop 0
	global_load_dwordx4 v[56:59], v[60:61], off nt
	s_nop 0
	global_load_dwordx4 v[60:63], v[64:65], off nt
	v_lshl_add_u64 v[64:65], v[64:65], 0, s[10:11]
	global_load_dwordx4 v[64:67], v[64:65], off nt
	s_cbranch_scc1 .LBB0_1081
	v_lshl_add_u64 v[70:71], v[68:69], 2, s[8:9]
	global_load_dwordx2 v[70:71], v[70:71], off
	s_waitcnt vmcnt(0)
	v_pk_mul_f32 v[6:7], v[6:7], v[70:71] op_sel_hi:[1,0]
	v_pk_mul_f32 v[4:5], v[4:5], v[70:71] op_sel_hi:[1,0]
	v_pk_mul_f32 v[10:11], v[10:11], v[70:71] op_sel:[0,1]
	v_pk_mul_f32 v[8:9], v[8:9], v[70:71] op_sel:[0,1]
	v_add_u32_e32 v70, 32, v68
	v_ashrrev_i32_e32 v71, 31, v70
	v_lshl_add_u64 v[70:71], v[70:71], 2, s[8:9]
	global_load_dwordx2 v[70:71], v[70:71], off
	s_waitcnt vmcnt(0)
	v_pk_mul_f32 v[14:15], v[14:15], v[70:71] op_sel_hi:[1,0]
	v_pk_mul_f32 v[12:13], v[12:13], v[70:71] op_sel_hi:[1,0]
	v_pk_mul_f32 v[18:19], v[18:19], v[70:71] op_sel:[0,1]
	v_pk_mul_f32 v[16:17], v[16:17], v[70:71] op_sel:[0,1]
	v_add_u32_e32 v70, 64, v68
	v_ashrrev_i32_e32 v71, 31, v70
	v_lshl_add_u64 v[70:71], v[70:71], 2, s[8:9]
	global_load_dwordx2 v[70:71], v[70:71], off
	s_waitcnt vmcnt(0)
	v_pk_mul_f32 v[22:23], v[22:23], v[70:71] op_sel_hi:[1,0]
	v_pk_mul_f32 v[20:21], v[20:21], v[70:71] op_sel_hi:[1,0]
	v_pk_mul_f32 v[26:27], v[26:27], v[70:71] op_sel:[0,1]
	v_pk_mul_f32 v[24:25], v[24:25], v[70:71] op_sel:[0,1]
	v_add_u32_e32 v70, 0x60, v68
	v_ashrrev_i32_e32 v71, 31, v70
	v_lshl_add_u64 v[70:71], v[70:71], 2, s[8:9]
	global_load_dwordx2 v[70:71], v[70:71], off
	s_waitcnt vmcnt(0)
	v_pk_mul_f32 v[30:31], v[30:31], v[70:71] op_sel_hi:[1,0]
	v_pk_mul_f32 v[28:29], v[28:29], v[70:71] op_sel_hi:[1,0]
	v_pk_mul_f32 v[34:35], v[34:35], v[70:71] op_sel:[0,1]
	v_pk_mul_f32 v[32:33], v[32:33], v[70:71] op_sel:[0,1]
	v_add_u32_e32 v70, 0x80, v68
	v_ashrrev_i32_e32 v71, 31, v70
	v_lshl_add_u64 v[70:71], v[70:71], 2, s[8:9]
	global_load_dwordx2 v[70:71], v[70:71], off
	s_waitcnt vmcnt(0)
	v_pk_mul_f32 v[38:39], v[38:39], v[70:71] op_sel_hi:[1,0]
	v_pk_mul_f32 v[36:37], v[36:37], v[70:71] op_sel_hi:[1,0]
	v_pk_mul_f32 v[42:43], v[42:43], v[70:71] op_sel:[0,1]
	v_pk_mul_f32 v[40:41], v[40:41], v[70:71] op_sel:[0,1]
	v_add_u32_e32 v70, 0xa0, v68
	v_ashrrev_i32_e32 v71, 31, v70
	v_lshl_add_u64 v[70:71], v[70:71], 2, s[8:9]
	global_load_dwordx2 v[70:71], v[70:71], off
	s_waitcnt vmcnt(0)
	v_pk_mul_f32 v[46:47], v[46:47], v[70:71] op_sel_hi:[1,0]
	v_pk_mul_f32 v[44:45], v[44:45], v[70:71] op_sel_hi:[1,0]
	v_pk_mul_f32 v[50:51], v[50:51], v[70:71] op_sel:[0,1]
	v_pk_mul_f32 v[48:49], v[48:49], v[70:71] op_sel:[0,1]
	v_add_u32_e32 v70, 0xc0, v68
	v_add_u32_e32 v68, 0xe0, v68
	v_ashrrev_i32_e32 v71, 31, v70
	v_ashrrev_i32_e32 v69, 31, v68
	v_lshl_add_u64 v[70:71], v[70:71], 2, s[8:9]
	v_lshl_add_u64 v[68:69], v[68:69], 2, s[8:9]
	global_load_dwordx2 v[70:71], v[70:71], off
	s_nop 0
	global_load_dwordx2 v[68:69], v[68:69], off
	s_waitcnt vmcnt(1)
	v_pk_mul_f32 v[54:55], v[54:55], v[70:71] op_sel_hi:[1,0]
	v_pk_mul_f32 v[52:53], v[52:53], v[70:71] op_sel_hi:[1,0]
	v_pk_mul_f32 v[58:59], v[58:59], v[70:71] op_sel:[0,1]
	v_pk_mul_f32 v[56:57], v[56:57], v[70:71] op_sel:[0,1]
	s_waitcnt vmcnt(0)
	v_pk_mul_f32 v[62:63], v[62:63], v[68:69] op_sel_hi:[1,0]
	v_pk_mul_f32 v[60:61], v[60:61], v[68:69] op_sel_hi:[1,0]
	v_pk_mul_f32 v[66:67], v[66:67], v[68:69] op_sel:[0,1]
	v_pk_mul_f32 v[64:65], v[64:65], v[68:69] op_sel:[0,1]

; __device__ __forceinline__ void tr_load(const TrJob& jb, int tile, int tid, f32x4 (&v)[8][2], int& k0, int& n0) {
;     const int nblk = (jb.N + 127) / 128, kt = tile / nblk, nt = tile - kt * nblk; k0 = 256 * kt; n0 = 128 * nt;
;     const int c4 = (tid & 15) + 16 * ((tid >> 6) & 1), rp = ((tid >> 4) & 3) + 4 * (tid >> 7);
;     int col = n0 + 4 * c4; col = col < jb.N - 4 ? col : jb.N - 4;
;     const float* wp = jb.W + (size_t)(k0 + 2 * rp) * jb.N + col;
; #pragma unroll
;     for (int i = 0; i < 8; ++i) { v[i][0] = *(const f32x4*)(wp + (size_t)(32 * i) * jb.N); v[i][1] = *(const f32x4*)(wp + (size_t)(32 * i + 1) * jb.N); }
;     if (jb.gain) {
; #pragma unroll
;         for (int i = 0; i < 8; ++i) { const float ga = jb.gain[k0 + 32 * i + 2 * rp], gb = jb.gain[k0 + 32 * i + 2 * rp + 1]; v[i][0] = v[i][0] * ga; v[i][1] = v[i][1] * gb; } }
; }
.LBB0_1614:
	s_add_i32 s6, s34, 0x7f
	s_lshr_b32 s6, s6, 7
	v_cvt_f32_u32_e32 v4, s6
	s_sub_i32 s9, 0, s6
	s_abs_i32 s8, s15
	s_ashr_i32 s7, s15, 31
	v_rcp_iflag_f32_e32 v4, v4
	v_lshrrev_b32_e32 v5, 4, v2
	v_ashrrev_i32_e32 v72, 5, v2
	v_bfi_b32 v5, 3, v5, v72
	v_mul_f32_e32 v4, 0x4f7ffffe, v4
	v_cvt_u32_f32_e32 v4, v4
	v_and_b32_e32 v71, 64, v2
	v_lshlrev_b32_e32 v78, 1, v5
	v_readfirstlane_b32 s12, v4
	s_mul_i32 s9, s9, s12
	s_mul_hi_u32 s9, s12, s9
	s_add_i32 s12, s12, s9
	s_mul_hi_u32 s9, s8, s12
	s_mul_i32 s12, s9, s6
	s_sub_i32 s8, s8, s12
	s_add_i32 s13, s9, 1
	s_sub_i32 s12, s8, s6
	s_cmp_ge_u32 s8, s6
	s_cselect_b32 s9, s13, s9
	s_cselect_b32 s8, s12, s8
	s_add_i32 s12, s9, 1
	s_cmp_ge_u32 s8, s6
	s_cselect_b32 s8, s12, s9
	s_xor_b32 s8, s8, s7
	s_sub_i32 s7, s8, s7
	s_mul_i32 s6, s7, s6
	s_sub_i32 s6, s15, s6
	v_lshlrev_b32_e32 v4, 2, v2
	s_lshl_b32 s14, s7, 8
	s_lshl_b32 s15, s6, 7
	v_and_or_b32 v77, v4, 60, v71
	v_or_b32_e32 v4, s15, v77
	s_add_i32 s6, s34, -4
	v_add_u32_e32 v68, s14, v78
	v_min_i32_e32 v4, s6, v4
	s_waitcnt vmcnt(12)
	v_mad_u64_u32 v[6:7], s[6:7], v68, s34, 0
	v_ashrrev_i32_e32 v69, 31, v68
	v_mov_b32_e32 v8, v7
	v_mad_u64_u32 v[8:9], s[6:7], v69, s34, v[8:9]
	v_mov_b32_e32 v7, v8
	v_lshl_add_u64 v[6:7], v[6:7], 2, s[4:5]
	v_ashrrev_i32_e32 v5, 31, v4
	v_lshl_add_u64 v[4:5], v[4:5], 2, v[6:7]
	s_lshl_b64 s[4:5], s[34:35], 2
	s_waitcnt vmcnt(11)
	v_lshl_add_u64 v[12:13], v[4:5], 0, s[4:5]
	s_mul_i32 s6, s34, 0x7c
	s_mov_b32 s7, s35
	global_load_dwordx4 v[4:7], v[4:5], off nt
	s_nop 0
	global_load_dwordx4 v[8:11], v[12:13], off nt
	v_lshl_add_u64 v[12:13], v[12:13], 0, s[6:7]
	s_waitcnt vmcnt(11)
	v_lshl_add_u64 v[20:21], v[12:13], 0, s[4:5]
	global_load_dwordx4 v[12:15], v[12:13], off nt
	s_nop 0
	global_load_dwordx4 v[16:19], v[20:21], off nt
	v_lshl_add_u64 v[20:21], v[20:21], 0, s[6:7]
	s_waitcnt vmcnt(12)
	v_lshl_add_u64 v[28:29], v[20:21], 0, s[4:5]
	global_load_dwordx4 v[20:23], v[20:21], off nt
	s_nop 0
	global_load_dwordx4 v[24:27], v[28:29], off nt
	v_lshl_add_u64 v[28:29], v[28:29], 0, s[6:7]
	s_waitcnt vmcnt(13)
	v_lshl_add_u64 v[36:37], v[28:29], 0, s[4:5]
	s_waitcnt vmcnt(12)
	v_lshl_add_u64 v[40:41], v[36:37], 0, s[6:7]
	s_waitcnt vmcnt(11)
	v_lshl_add_u64 v[44:45], v[40:41], 0, s[4:5]
	s_waitcnt vmcnt(10)
	v_lshl_add_u64 v[48:49], v[44:45], 0, s[6:7]
	s_waitcnt vmcnt(9)
	v_lshl_add_u64 v[52:53], v[48:49], 0, s[4:5]
	s_waitcnt vmcnt(8)
	v_lshl_add_u64 v[56:57], v[52:53], 0, s[6:7]
	s_waitcnt vmcnt(7)
	v_lshl_add_u64 v[60:61], v[56:57], 0, s[4:5]
	s_waitcnt vmcnt(6)
	v_lshl_add_u64 v[64:65], v[60:61], 0, s[6:7]
	global_load_dwordx4 v[28:31], v[28:29], off nt
	s_nop 0
	global_load_dwordx4 v[32:35], v[36:37], off nt
	s_cmp_eq_u64 s[10:11], 0
	global_load_dwordx4 v[36:39], v[40:41], off nt
	s_nop 0
	global_load_dwordx4 v[40:43], v[44:45], off nt
	s_nop 0
	global_load_dwordx4 v[44:47], v[48:49], off nt
	s_nop 0
	global_load_dwordx4 v[48:51], v[52:53], off nt
	s_nop 0
	global_load_dwordx4 v[52:55], v[56:57], off nt
	s_nop 0
	global_load_dwordx4 v[56:59], v[60:61], off nt
	s_nop 0
	global_load_dwordx4 v[60:63], v[64:65], off nt
	v_lshl_add_u64 v[64:65], v[64:65], 0, s[4:5]
	global_load_dwordx4 v[64:67], v[64:65], off nt
	s_cbranch_scc1 .LBB0_1616
	v_lshl_add_u64 v[68:69], v[68:69], 2, s[10:11]
	global_load_dwordx2 v[74:75], v[68:69], off
	s_waitcnt vmcnt(0)
	v_pk_mul_f32 v[6:7], v[6:7], v[74:75] op_sel_hi:[1,0]
	v_pk_mul_f32 v[4:5], v[4:5], v[74:75] op_sel_hi:[1,0]
	v_pk_mul_f32 v[10:11], v[10:11], v[74:75] op_sel:[0,1]
	v_pk_mul_f32 v[8:9], v[8:9], v[74:75] op_sel:[0,1]
	global_load_dwordx2 v[74:75], v[68:69], off offset:128
	s_waitcnt vmcnt(0)
	v_pk_mul_f32 v[14:15], v[14:15], v[74:75] op_sel_hi:[1,0]
	v_pk_mul_f32 v[12:13], v[12:13], v[74:75] op_sel_hi:[1,0]
	v_pk_mul_f32 v[18:19], v[18:19], v[74:75] op_sel:[0,1]
	v_pk_mul_f32 v[16:17], v[16:17], v[74:75] op_sel:[0,1]
	global_load_dwordx2 v[74:75], v[68:69], off offset:256
	s_waitcnt vmcnt(0)
	v_pk_mul_f32 v[22:23], v[22:23], v[74:75] op_sel_hi:[1,0]
	v_pk_mul_f32 v[20:21], v[20:21], v[74:75] op_sel_hi:[1,0]
	v_pk_mul_f32 v[26:27], v[26:27], v[74:75] op_sel:[0,1]
	v_pk_mul_f32 v[24:25], v[24:25], v[74:75] op_sel:[0,1]
	global_load_dwordx2 v[74:75], v[68:69], off offset:384
	s_waitcnt vmcnt(0)
	v_pk_mul_f32 v[30:31], v[30:31], v[74:75] op_sel_hi:[1,0]
	v_pk_mul_f32 v[28:29], v[28:29], v[74:75] op_sel_hi:[1,0]
	v_pk_mul_f32 v[34:35], v[34:35], v[74:75] op_sel:[0,1]
	v_pk_mul_f32 v[32:33], v[32:33], v[74:75] op_sel:[0,1]
	global_load_dwordx2 v[74:75], v[68:69], off offset:512
	s_waitcnt vmcnt(0)
	v_pk_mul_f32 v[38:39], v[38:39], v[74:75] op_sel_hi:[1,0]
	v_pk_mul_f32 v[36:37], v[36:37], v[74:75] op_sel_hi:[1,0]
	v_pk_mul_f32 v[42:43], v[42:43], v[74:75] op_sel:[0,1]
	v_pk_mul_f32 v[40:41], v[40:41], v[74:75] op_sel:[0,1]
	global_load_dwordx2 v[74:75], v[68:69], off offset:640
	s_waitcnt vmcnt(0)
	v_pk_mul_f32 v[46:47], v[46:47], v[74:75] op_sel_hi:[1,0]
	v_pk_mul_f32 v[44:45], v[44:45], v[74:75] op_sel_hi:[1,0]
	v_pk_mul_f32 v[50:51], v[50:51], v[74:75] op_sel:[0,1]
	v_pk_mul_f32 v[48:49], v[48:49], v[74:75] op_sel:[0,1]
	global_load_dwordx2 v[74:75], v[68:69], off offset:768
	s_waitcnt vmcnt(0)
	v_pk_mul_f32 v[54:55], v[54:55], v[74:75] op_sel_hi:[1,0]
	global_load_dwordx2 v[68:69], v[68:69], off offset:896
	v_pk_mul_f32 v[52:53], v[52:53], v[74:75] op_sel_hi:[1,0]
	v_pk_mul_f32 v[58:59], v[58:59], v[74:75] op_sel:[0,1]
	v_pk_mul_f32 v[56:57], v[56:57], v[74:75] op_sel:[0,1]
	s_waitcnt vmcnt(0)
	v_pk_mul_f32 v[62:63], v[62:63], v[68:69] op_sel_hi:[1,0]
	v_pk_mul_f32 v[60:61], v[60:61], v[68:69] op_sel_hi:[1,0]
	v_pk_mul_f32 v[66:67], v[66:67], v[68:69] op_sel:[0,1]
	v_pk_mul_f32 v[64:65], v[64:65], v[68:69] op_sel:[0,1]
